# MFMA blocks of the K-loops on 8-byte boundaries and never starting exactly at a cache-line start (opening barrier and first MFMA in one line)
# speedup vs baseline: 1.0035x; 1.0035x over previous
; #define PG8_STAGEA(bufoff, gbase, voff) PG8_STAGE_X(bufoff, gbase, voff, AUXA)
; #define PG8_STR(x) PG8_STR2(x)
;     ...
;         const bool has_next = S.next(ui + 1, nxt);
;         const char* nA = has_next ? (const char*)g.A + (size_t)nxt.pm * tstepA : cA; const char* nB = has_next ? (const char*)g.Bt + (size_t)nxt.pn * tstepB : cB;
;         int t0 = 0;
;         if constexpr (SP2 && GEMM_RELAX == 1) { if (ui > 0) {
;             const char* a1 = cA + kstepA; const char* a2 = cA + 2 * kstepA; const char* b2 = cB + 2 * kstepB; const char* a3 = a2 + kstepA; const char* b3 = b2 + kstepB;
;             PG8_LDB(B0, 0, 0); PG8_LDB(B1, 0, 1); PG8_SCHED; PG8_LDA(At, 0, 0); PG8_STAGEA(PG8_SA(1, 1), a1 + hstepA, voffA);
;             PG8_WAIT_V(24); PG8_WAIT_L(0); PG8_BAR; PG8_MMA(0, 0, At, B0); PG8_MMA(0, 1, At, B1); PG8_BAR; PG8_SCHED;
;             PG8_LDA(At, 0, 1); PG8_STAGEB(PG8_SB(0, 0), b2, voffB); PG8_STAGEB(PG8_SB(0, 1), b2 + hstepB, voffB); PG8_STAGEA(PG8_SA(0, 0), a2, voffA);
;             PG8_WAIT_V(24); PG8_WAIT_L(0); PG8_BAR; PG8_MMA(1, 0, At, B0); PG8_MMA(1, 1, At, B1); PG8_BAR; PG8_SCHED;
;             PG8_LDB(B0, 1, 0); PG8_LDB(B1, 1, 1); PG8_SCHED; PG8_LDA(At, 1, 0); PG8_STAGEA(PG8_SA(0, 1), a2 + hstepA, voffA);
;             PG8_WAIT_V(8); PG8_WAIT_L(0); PG8_BAR; PG8_MMA(0, 0, At, B0); PG8_MMA(0, 1, At, B1); PG8_BAR; PG8_SCHED;
;             PG8_LDA(At, 1, 1); PG8_STAGEB(PG8_SB(1, 0), b3, voffB); PG8_STAGEB(PG8_SB(1, 1), b3 + hstepB, voffB); PG8_STAGEA(PG8_SA(1, 0), a3, voffA);
;             PG8_WAIT_V(8); PG8_WAIT_L(0); PG8_BAR; PG8_MMA(1, 0, At, B0); PG8_MMA(1, 1, At, B1); PG8_BAR; PG8_SCHED;
;             t0 = 2; } }
;     ...
;         asm volatile(".p2align " PG8_STR(GEMM_LOOP_ALIGN) ::: "memory");
;     ...
;         for (int t = t0; t < nt; t += 2) {
;             const bool last = (t == nt - 2);
;             const char* a1 = cA + (size_t)(t + 1) * kstepA;
;             const char* a2 = last ? nA : cA + (size_t)(t + 2) * kstepA; const char* b2 = last ? nB : cB + (size_t)(t + 2) * kstepB;
;             const char* a3 = a2 + kstepA; const char* b3 = b2 + kstepB;
;             if (last && has_next) S.a_ready(nxt);
;             if constexpr (SP2) {
;             PG8_LDB(B0, 0, 0); PG8_LDB(B1, 0, 1); PG8_SCHED; PG8_LDA(At, 0, 0); PG8_STAGEA(PG8_SA(1, 1), a1 + hstepA, voffA);
;     ...
;             const int relax = __builtin_amdgcn_readfirstlane((t == 0 && ui > 0) ? 1 : 0);
.LBB0_128:
	s_ashr_i32 s37, s36, 31
	s_lshl_b64 s[4:5], s[36:37], 21
	s_add_u32 s38, s56, s4
	s_addc_u32 s39, s57, s5
	s_and_b64 s[4:5], s[6:7], exec
	s_cselect_b32 s4, s39, s1
	s_cselect_b32 s5, s38, s0
	s_ashr_i32 s27, s26, 31
	s_lshl_b64 s[8:9], s[26:27], 21
	s_add_u32 s40, s43, s8
	s_addc_u32 s41, s50, s9
	s_and_b64 s[8:9], s[6:7], exec
	s_cselect_b32 s16, s41, s11
	s_cselect_b32 s17, s40, s10
	s_add_u32 s8, s0, 0x100080
	s_addc_u32 s9, s1, 0
	s_add_u32 s0, s10, 0x100
	s_addc_u32 s1, s11, 0
	s_mov_b32 s27, -2
	s_add_u32 s10, s8, 0xfff00080
	s_addc_u32 s11, s9, -1
	s_add_i32 s18, 0, 0x10000
	s_cmp_eq_u32 s27, 60
	s_cselect_b32 s15, s4, s11
	s_cselect_b32 s14, s5, s10
	v_add_u32_e32 v16, s18, v167
	s_cselect_b32 s11, s16, s1
	s_cselect_b32 s10, s17, s0
	s_add_i32 s20, 0, 0x14000
	s_waitcnt lgkmcnt(0)
	ds_read_b128 v[130:133], v16
	ds_read_b128 v[134:137], v16 offset:1024
	ds_read_b128 v[152:155], v16 offset:2048
	ds_read_b128 v[156:159], v16 offset:3072
	v_add_u32_e32 v16, s20, v167
	ds_read_b128 v[160:163], v16
	ds_read_b128 v[174:177], v16 offset:1024
	ds_read_b128 v[178:181], v16 offset:2048
	ds_read_b128 v[182:185], v16 offset:3072
	v_lshl_add_u64 v[164:165], s[8:9], 0, v[148:149]
	s_add_i32 m0, s51, 0xc000
	ds_read_b128 v[186:189], v172
	ds_read_b128 v[190:193], v172 offset:1024
	ds_read_b128 v[194:197], v172 offset:2048
	ds_read_b128 v[198:201], v172 offset:3072
	ds_read_b128 v[202:205], v172 offset:4096
	ds_read_b128 v[206:209], v172 offset:5120
	ds_read_b128 v[210:213], v172 offset:6144
	ds_read_b128 v[214:217], v172 offset:7168
	global_load_lds_dwordx4 v[164:165], off
	v_lshl_add_u64 v[164:165], s[8:9], 0, v[150:151]
	s_add_i32 m0, s51, 0xe000
	s_nop 0
	global_load_lds_dwordx4 v[164:165], off
	s_waitcnt vmcnt(8)
	s_waitcnt lgkmcnt(0)
	s_setprio 1
	s_barrier
	v_mfma_f32_16x16x32_bf16 v[126:129], v[130:133], v[186:189], 0
	v_mfma_f32_16x16x32_bf16 v[122:125], v[152:155], v[186:189], 0
	v_mfma_f32_16x16x32_bf16 v[110:113], v[130:133], v[194:197], 0
	v_mfma_f32_16x16x32_bf16 v[106:109], v[152:155], v[194:197], 0
	v_mfma_f32_16x16x32_bf16 v[94:97], v[130:133], v[202:205], 0
	v_mfma_f32_16x16x32_bf16 v[90:93], v[152:155], v[202:205], 0
	v_mfma_f32_16x16x32_bf16 v[78:81], v[130:133], v[210:213], 0
	v_mfma_f32_16x16x32_bf16 v[74:77], v[152:155], v[210:213], 0
	v_mfma_f32_16x16x32_bf16 v[126:129], v[134:137], v[190:193], v[126:129]
	v_mfma_f32_16x16x32_bf16 v[122:125], v[156:159], v[190:193], v[122:125]
	v_mfma_f32_16x16x32_bf16 v[110:113], v[134:137], v[198:201], v[110:113]
	v_mfma_f32_16x16x32_bf16 v[106:109], v[156:159], v[198:201], v[106:109]
	v_mfma_f32_16x16x32_bf16 v[94:97], v[134:137], v[206:209], v[94:97]
	v_mfma_f32_16x16x32_bf16 v[90:93], v[156:159], v[206:209], v[90:93]
	v_mfma_f32_16x16x32_bf16 v[78:81], v[134:137], v[214:217], v[78:81]
	v_mfma_f32_16x16x32_bf16 v[74:77], v[156:159], v[214:217], v[74:77]
	v_mfma_f32_16x16x32_bf16 v[118:121], v[160:163], v[186:189], 0
	v_mfma_f32_16x16x32_bf16 v[114:117], v[178:181], v[186:189], 0
	v_mfma_f32_16x16x32_bf16 v[102:105], v[160:163], v[194:197], 0
	v_mfma_f32_16x16x32_bf16 v[98:101], v[178:181], v[194:197], 0
	v_mfma_f32_16x16x32_bf16 v[86:89], v[160:163], v[202:205], 0
	v_mfma_f32_16x16x32_bf16 v[82:85], v[178:181], v[202:205], 0
	v_mfma_f32_16x16x32_bf16 v[70:73], v[160:163], v[210:213], 0
	v_mfma_f32_16x16x32_bf16 v[66:69], v[178:181], v[210:213], 0
	v_mfma_f32_16x16x32_bf16 v[118:121], v[174:177], v[190:193], v[118:121]
	v_mfma_f32_16x16x32_bf16 v[114:117], v[182:185], v[190:193], v[114:117]
	v_mfma_f32_16x16x32_bf16 v[102:105], v[174:177], v[198:201], v[102:105]
	v_mfma_f32_16x16x32_bf16 v[98:101], v[182:185], v[198:201], v[98:101]
	v_mfma_f32_16x16x32_bf16 v[86:89], v[174:177], v[206:209], v[86:89]
	v_mfma_f32_16x16x32_bf16 v[82:85], v[182:185], v[206:209], v[82:85]
	v_mfma_f32_16x16x32_bf16 v[70:73], v[174:177], v[214:217], v[70:73]
	v_mfma_f32_16x16x32_bf16 v[66:69], v[182:185], v[214:217], v[66:69]
	s_barrier
	s_setprio 0
	s_add_i32 s18, s18, s42
	v_lshl_add_u64 v[164:165], s[10:11], 0, v[142:143]
	s_mov_b32 m0, s18
	ds_read_b128 v[186:189], v172 offset:16384
	ds_read_b128 v[190:193], v172 offset:17408
	ds_read_b128 v[194:197], v172 offset:18432
	ds_read_b128 v[198:201], v172 offset:19456
	ds_read_b128 v[202:205], v172 offset:20480
	ds_read_b128 v[206:209], v172 offset:21504
	ds_read_b128 v[210:213], v172 offset:22528
	ds_read_b128 v[214:217], v172 offset:23552
	global_load_lds_dwordx4 v[164:165], off
	s_add_i32 m0, s18, 0x2000
	s_add_u32 s18, s10, 0x100000
	v_lshl_add_u64 v[218:219], s[10:11], 0, v[138:139]
	s_addc_u32 s19, s11, 0
	s_add_i32 s20, s20, s42
	global_load_lds_dwordx4 v[218:219], off
	v_lshl_add_u64 v[220:221], s[18:19], 0, v[142:143]
	s_mov_b32 m0, s20
	v_lshl_add_u64 v[222:223], s[14:15], 0, v[140:141]
	global_load_lds_dwordx4 v[220:221], off
	v_lshl_add_u64 v[220:221], s[18:19], 0, v[138:139]
	s_add_i32 m0, s20, 0x2000
	s_nop 0
	global_load_lds_dwordx4 v[220:221], off
	v_lshl_add_u64 v[220:221], s[14:15], 0, v[144:145]
	s_mov_b32 m0, s51
	s_nop 0
	global_load_lds_dwordx4 v[220:221], off
	s_mov_b32 m0, s68
	s_nop 0
	global_load_lds_dwordx4 v[222:223], off
	s_waitcnt vmcnt(8)
	s_waitcnt lgkmcnt(0)
	s_nop 0
	s_nop 0
	s_setprio 1
	s_barrier
; #define PG8_STAGEA(bufoff, gbase, voff) PG8_STAGE_X(bufoff, gbase, voff, AUXA)
; #define PG8_LDA(dst, b, h) do { _Pragma("unroll") for (int m = 0; m < 4; ++m) _Pragma("unroll") for (int k = 0; k < 2; ++k) dst[m][k] = *(const PG8_LAS bf16x8*)(lds + PG8_SA(b, h) + aoff + m * 2048 + k * 1024); } while (0)
; #define PG8_LDB(dst, b, h) do { _Pragma("unroll") for (int n = 0; n < 2; ++n) _Pragma("unroll") for (int k = 0; k < 2; ++k) dst[n][k] = *(const PG8_LAS bf16x8*)(lds + PG8_SB(b, h) + boff + n * 2048 + k * 1024); } while (0)
; #define PG8_MMA(ai, bj, At, Bt) do { if (GEMM_PRIO_MODE == 0) __builtin_amdgcn_s_setprio(1); PG8_MMA_LOOPS \
;         acc[ai][bj][m][n] = __builtin_amdgcn_mfma_f32_16x16x32_bf16(Bt[n][k], At[m][k], acc[ai][bj][m][n], 0, 0, 0); if (GEMM_PRIO_MODE == 0) __builtin_amdgcn_s_setprio(0); } while (0)
; #define PG8_WAIT_V(n) asm volatile("s_waitcnt vmcnt(" #n ")" ::: "memory")
; #define PG8_WAIT_L(n) asm volatile("s_waitcnt lgkmcnt(" #n ")" ::: "memory")
; #define PG8_BAR __builtin_amdgcn_s_barrier()
; #define PG8_SCHED __builtin_amdgcn_sched_barrier(0)
;     ...
;             PG8_WAIT_V(8); PG8_WAIT_L(0); PG8_BAR; PG8_MMA(1, 0, At, B0); PG8_MMA(1, 1, At, B1); PG8_BAR; PG8_SCHED;
;     ...
;             PG8_LDB(B0, 1, 0); PG8_LDB(B1, 1, 1); PG8_SCHED; PG8_LDA(At, 1, 0); PG8_STAGEA(PG8_SA(0, 1), a2 + hstepA, voffA);
;             PG8_WAIT_V(8); PG8_WAIT_L(0); PG8_BAR; PG8_MMA(0, 0, At, B0); PG8_MMA(0, 1, At, B1); PG8_BAR; PG8_SCHED;
	v_mfma_f32_16x16x32_bf16 v[62:65], v[130:133], v[186:189], 0
	v_mfma_f32_16x16x32_bf16 v[58:61], v[152:155], v[186:189], 0
	v_mfma_f32_16x16x32_bf16 v[46:49], v[130:133], v[194:197], 0
	v_mfma_f32_16x16x32_bf16 v[42:45], v[152:155], v[194:197], 0
	v_mfma_f32_16x16x32_bf16 v[30:33], v[130:133], v[202:205], 0
	v_mfma_f32_16x16x32_bf16 v[26:29], v[152:155], v[202:205], 0
	v_mfma_f32_16x16x32_bf16 v[12:15], v[130:133], v[210:213], 0
	v_mfma_f32_16x16x32_bf16 v[8:11], v[152:155], v[210:213], 0
	v_mfma_f32_16x16x32_bf16 v[62:65], v[134:137], v[190:193], v[62:65]
	v_mfma_f32_16x16x32_bf16 v[58:61], v[156:159], v[190:193], v[58:61]
	v_mfma_f32_16x16x32_bf16 v[46:49], v[134:137], v[198:201], v[46:49]
	v_mfma_f32_16x16x32_bf16 v[42:45], v[156:159], v[198:201], v[42:45]
	v_mfma_f32_16x16x32_bf16 v[30:33], v[134:137], v[206:209], v[30:33]
	v_mfma_f32_16x16x32_bf16 v[26:29], v[156:159], v[206:209], v[26:29]
	v_mfma_f32_16x16x32_bf16 v[12:15], v[134:137], v[214:217], v[12:15]
	v_mfma_f32_16x16x32_bf16 v[8:11], v[156:159], v[214:217], v[8:11]
	v_mfma_f32_16x16x32_bf16 v[54:57], v[160:163], v[186:189], 0
	v_mfma_f32_16x16x32_bf16 v[50:53], v[178:181], v[186:189], 0
	v_mfma_f32_16x16x32_bf16 v[38:41], v[160:163], v[194:197], 0
	v_mfma_f32_16x16x32_bf16 v[34:37], v[178:181], v[194:197], 0
	v_mfma_f32_16x16x32_bf16 v[22:25], v[160:163], v[202:205], 0
	v_mfma_f32_16x16x32_bf16 v[18:21], v[178:181], v[202:205], 0
	v_mfma_f32_16x16x32_bf16 v[4:7], v[160:163], v[210:213], 0
	v_mfma_f32_16x16x32_bf16 v[0:3], v[178:181], v[210:213], 0
	v_mfma_f32_16x16x32_bf16 v[54:57], v[174:177], v[190:193], v[54:57]
	v_mfma_f32_16x16x32_bf16 v[50:53], v[182:185], v[190:193], v[50:53]
	v_mfma_f32_16x16x32_bf16 v[38:41], v[174:177], v[198:201], v[38:41]
	v_mfma_f32_16x16x32_bf16 v[34:37], v[182:185], v[198:201], v[34:37]
	v_mfma_f32_16x16x32_bf16 v[22:25], v[174:177], v[206:209], v[22:25]
	v_mfma_f32_16x16x32_bf16 v[18:21], v[182:185], v[206:209], v[18:21]
	v_mfma_f32_16x16x32_bf16 v[4:7], v[174:177], v[214:217], v[4:7]
	v_mfma_f32_16x16x32_bf16 v[0:3], v[182:185], v[214:217], v[0:3]
	s_barrier
	s_setprio 0
	s_add_i32 s18, 0, 0x18000
	v_add_u32_e32 v16, s18, v167
	s_add_i32 s19, 0, 0x1c000
	ds_read_b128 v[130:133], v16
	ds_read_b128 v[134:137], v16 offset:1024
	ds_read_b128 v[152:155], v16 offset:2048
	ds_read_b128 v[156:159], v16 offset:3072
	v_add_u32_e32 v16, s19, v167
	ds_read_b128 v[160:163], v16
	ds_read_b128 v[174:177], v16 offset:1024
	ds_read_b128 v[178:181], v16 offset:2048
	ds_read_b128 v[182:185], v16 offset:3072
	s_add_u32 s14, s14, 0x100000
	s_addc_u32 s15, s15, 0
	s_mov_b32 m0, s69
	v_lshl_add_u64 v[224:225], s[14:15], 0, v[144:145]
	ds_read_b128 v[186:189], v172 offset:32768
	ds_read_b128 v[190:193], v172 offset:33792
	ds_read_b128 v[194:197], v172 offset:34816
	ds_read_b128 v[198:201], v172 offset:35840
	ds_read_b128 v[202:205], v172 offset:36864
	ds_read_b128 v[206:209], v172 offset:37888
	ds_read_b128 v[210:213], v172 offset:38912
	ds_read_b128 v[214:217], v172 offset:39936
	global_load_lds_dwordx4 v[224:225], off
	v_lshl_add_u64 v[224:225], s[14:15], 0, v[140:141]
	s_mov_b32 m0, s72
	s_nop 0
	global_load_lds_dwordx4 v[224:225], off
	s_waitcnt vmcnt(8)
	s_waitcnt lgkmcnt(0)
	s_setprio 1
	s_barrier
	v_mfma_f32_16x16x32_bf16 v[126:129], v[130:133], v[186:189], v[126:129]
	v_mfma_f32_16x16x32_bf16 v[122:125], v[152:155], v[186:189], v[122:125]
	v_mfma_f32_16x16x32_bf16 v[110:113], v[130:133], v[194:197], v[110:113]
	v_mfma_f32_16x16x32_bf16 v[106:109], v[152:155], v[194:197], v[106:109]
	v_mfma_f32_16x16x32_bf16 v[94:97], v[130:133], v[202:205], v[94:97]
	v_mfma_f32_16x16x32_bf16 v[90:93], v[152:155], v[202:205], v[90:93]
	v_mfma_f32_16x16x32_bf16 v[78:81], v[130:133], v[210:213], v[78:81]
	v_mfma_f32_16x16x32_bf16 v[74:77], v[152:155], v[210:213], v[74:77]
	v_mfma_f32_16x16x32_bf16 v[126:129], v[134:137], v[190:193], v[126:129]
	v_mfma_f32_16x16x32_bf16 v[122:125], v[156:159], v[190:193], v[122:125]
	v_mfma_f32_16x16x32_bf16 v[110:113], v[134:137], v[198:201], v[110:113]
	v_mfma_f32_16x16x32_bf16 v[106:109], v[156:159], v[198:201], v[106:109]
	v_mfma_f32_16x16x32_bf16 v[94:97], v[134:137], v[206:209], v[94:97]
	v_mfma_f32_16x16x32_bf16 v[90:93], v[156:159], v[206:209], v[90:93]
	v_mfma_f32_16x16x32_bf16 v[78:81], v[134:137], v[214:217], v[78:81]
	v_mfma_f32_16x16x32_bf16 v[74:77], v[156:159], v[214:217], v[74:77]
	v_mfma_f32_16x16x32_bf16 v[118:121], v[160:163], v[186:189], v[118:121]
	v_mfma_f32_16x16x32_bf16 v[114:117], v[178:181], v[186:189], v[114:117]
	v_mfma_f32_16x16x32_bf16 v[102:105], v[160:163], v[194:197], v[102:105]
	v_mfma_f32_16x16x32_bf16 v[98:101], v[178:181], v[194:197], v[98:101]
	v_mfma_f32_16x16x32_bf16 v[86:89], v[160:163], v[202:205], v[86:89]
	v_mfma_f32_16x16x32_bf16 v[82:85], v[178:181], v[202:205], v[82:85]
	v_mfma_f32_16x16x32_bf16 v[70:73], v[160:163], v[210:213], v[70:73]
	v_mfma_f32_16x16x32_bf16 v[66:69], v[178:181], v[210:213], v[66:69]
	v_mfma_f32_16x16x32_bf16 v[118:121], v[174:177], v[190:193], v[118:121]
	v_mfma_f32_16x16x32_bf16 v[114:117], v[182:185], v[190:193], v[114:117]
	v_mfma_f32_16x16x32_bf16 v[102:105], v[174:177], v[198:201], v[102:105]
	v_mfma_f32_16x16x32_bf16 v[98:101], v[182:185], v[198:201], v[98:101]
	v_mfma_f32_16x16x32_bf16 v[86:89], v[174:177], v[206:209], v[86:89]
	v_mfma_f32_16x16x32_bf16 v[82:85], v[182:185], v[206:209], v[82:85]
	v_mfma_f32_16x16x32_bf16 v[70:73], v[174:177], v[214:217], v[70:73]
	v_mfma_f32_16x16x32_bf16 v[66:69], v[182:185], v[214:217], v[66:69]
	s_barrier
; #define PG8_STAGEA(bufoff, gbase, voff) PG8_STAGE_X(bufoff, gbase, voff, AUXA)
; #define PG8_STAGEB(bufoff, gbase, voff) PG8_STAGE_X(bufoff, gbase, voff, AUXB)
; #define PG8_LDA(dst, b, h) do { _Pragma("unroll") for (int m = 0; m < 4; ++m) _Pragma("unroll") for (int k = 0; k < 2; ++k) dst[m][k] = *(const PG8_LAS bf16x8*)(lds + PG8_SA(b, h) + aoff + m * 2048 + k * 1024); } while (0)
; #define PG8_MMA(ai, bj, At, Bt) do { if (GEMM_PRIO_MODE == 0) __builtin_amdgcn_s_setprio(1); PG8_MMA_LOOPS \
;         acc[ai][bj][m][n] = __builtin_amdgcn_mfma_f32_16x16x32_bf16(Bt[n][k], At[m][k], acc[ai][bj][m][n], 0, 0, 0); if (GEMM_PRIO_MODE == 0) __builtin_amdgcn_s_setprio(0); } while (0)
; #define PG8_WAIT_V(n) asm volatile("s_waitcnt vmcnt(" #n ")" ::: "memory")
; #define PG8_WAIT_L(n) asm volatile("s_waitcnt lgkmcnt(" #n ")" ::: "memory")
; #define PG8_BAR __builtin_amdgcn_s_barrier()
; #define PG8_SCHED __builtin_amdgcn_sched_barrier(0)
;     ...
;             PG8_LDA(At, 1, 1); PG8_STAGEB(PG8_SB(1, 0), b3, voffB); PG8_STAGEB(PG8_SB(1, 1), b3 + hstepB, voffB); PG8_STAGEA(PG8_SA(1, 0), a3, voffA);
;             PG8_WAIT_V(8); PG8_WAIT_L(0); PG8_BAR; PG8_MMA(1, 0, At, B0); PG8_MMA(1, 1, At, B1); PG8_BAR; PG8_SCHED;
	s_setprio 0
	s_add_i32 s14, s18, s42
	v_lshl_add_u64 v[164:165], v[164:165], 0, s[86:87]
	s_mov_b32 m0, s14
	ds_read_b128 v[186:189], v172 offset:49152
	ds_read_b128 v[190:193], v172 offset:50176
	ds_read_b128 v[194:197], v172 offset:51200
	ds_read_b128 v[198:201], v172 offset:52224
	ds_read_b128 v[202:205], v172 offset:53248
	ds_read_b128 v[206:209], v172 offset:54272
	ds_read_b128 v[210:213], v172 offset:55296
	ds_read_b128 v[214:217], v172 offset:56320
	global_load_lds_dwordx4 v[164:165], off
	s_add_i32 m0, s14, 0x2000
	s_add_u32 s10, s10, 0x100080
	v_lshl_add_u64 v[164:165], v[218:219], 0, s[86:87]
	s_addc_u32 s11, s11, 0
	s_add_i32 s14, s19, s42
	global_load_lds_dwordx4 v[164:165], off
	v_lshl_add_u64 v[164:165], s[10:11], 0, v[142:143]
	s_mov_b32 m0, s14
	s_nop 0
	global_load_lds_dwordx4 v[164:165], off
	v_lshl_add_u64 v[164:165], s[10:11], 0, v[138:139]
	s_add_i32 m0, s14, 0x2000
	s_nop 0
	global_load_lds_dwordx4 v[164:165], off
	v_lshl_add_u64 v[164:165], v[220:221], 0, s[86:87]
	s_mov_b32 m0, s73
	s_nop 0
	global_load_lds_dwordx4 v[164:165], off
	v_lshl_add_u64 v[164:165], v[222:223], 0, s[86:87]
	s_mov_b32 m0, s82
	s_nop 0
	global_load_lds_dwordx4 v[164:165], off
	s_waitcnt vmcnt(8)
	s_waitcnt lgkmcnt(0)
	s_nop 0
	s_setprio 1
	s_barrier
	v_mfma_f32_16x16x32_bf16 v[62:65], v[130:133], v[186:189], v[62:65]
	v_mfma_f32_16x16x32_bf16 v[58:61], v[152:155], v[186:189], v[58:61]
	v_mfma_f32_16x16x32_bf16 v[46:49], v[130:133], v[194:197], v[46:49]
	v_mfma_f32_16x16x32_bf16 v[42:45], v[152:155], v[194:197], v[42:45]
	v_mfma_f32_16x16x32_bf16 v[30:33], v[130:133], v[202:205], v[30:33]
	v_mfma_f32_16x16x32_bf16 v[26:29], v[152:155], v[202:205], v[26:29]
	v_mfma_f32_16x16x32_bf16 v[12:15], v[130:133], v[210:213], v[12:15]
	v_mfma_f32_16x16x32_bf16 v[8:11], v[152:155], v[210:213], v[8:11]
	v_mfma_f32_16x16x32_bf16 v[62:65], v[134:137], v[190:193], v[62:65]
	v_mfma_f32_16x16x32_bf16 v[58:61], v[156:159], v[190:193], v[58:61]
	v_mfma_f32_16x16x32_bf16 v[46:49], v[134:137], v[198:201], v[46:49]
	v_mfma_f32_16x16x32_bf16 v[42:45], v[156:159], v[198:201], v[42:45]
	v_mfma_f32_16x16x32_bf16 v[30:33], v[134:137], v[206:209], v[30:33]
	v_mfma_f32_16x16x32_bf16 v[26:29], v[156:159], v[206:209], v[26:29]
	v_mfma_f32_16x16x32_bf16 v[12:15], v[134:137], v[214:217], v[12:15]
	v_mfma_f32_16x16x32_bf16 v[8:11], v[156:159], v[214:217], v[8:11]
	v_mfma_f32_16x16x32_bf16 v[54:57], v[160:163], v[186:189], v[54:57]
	v_mfma_f32_16x16x32_bf16 v[50:53], v[178:181], v[186:189], v[50:53]
	v_mfma_f32_16x16x32_bf16 v[38:41], v[160:163], v[194:197], v[38:41]
	v_mfma_f32_16x16x32_bf16 v[34:37], v[178:181], v[194:197], v[34:37]
	v_mfma_f32_16x16x32_bf16 v[22:25], v[160:163], v[202:205], v[22:25]
	v_mfma_f32_16x16x32_bf16 v[18:21], v[178:181], v[202:205], v[18:21]
	v_mfma_f32_16x16x32_bf16 v[4:7], v[160:163], v[210:213], v[4:7]
	v_mfma_f32_16x16x32_bf16 v[0:3], v[178:181], v[210:213], v[0:3]
	v_mfma_f32_16x16x32_bf16 v[54:57], v[174:177], v[190:193], v[54:57]
	v_mfma_f32_16x16x32_bf16 v[50:53], v[182:185], v[190:193], v[50:53]
	v_mfma_f32_16x16x32_bf16 v[38:41], v[174:177], v[198:201], v[38:41]
	v_mfma_f32_16x16x32_bf16 v[34:37], v[182:185], v[198:201], v[34:37]
	v_mfma_f32_16x16x32_bf16 v[22:25], v[174:177], v[206:209], v[22:25]
	v_mfma_f32_16x16x32_bf16 v[18:21], v[182:185], v[206:209], v[18:21]
	v_mfma_f32_16x16x32_bf16 v[4:7], v[174:177], v[214:217], v[4:7]
	v_mfma_f32_16x16x32_bf16 v[0:3], v[182:185], v[214:217], v[0:3]
	s_barrier
	s_setprio 0
	s_add_i32 s27, s27, 2
	s_add_u32 s8, s8, 0x100
	s_addc_u32 s9, s9, 0
	s_add_u32 s0, s0, 0x100
	s_addc_u32 s1, s1, 0

; #define PG8_STAGEA(bufoff, gbase, voff) PG8_STAGE_X(bufoff, gbase, voff, AUXA)
; #define PG8_STR(x) PG8_STR2(x)
;     ...
;         const bool has_next = S.next(ui + 1, nxt);
;         const char* nA = has_next ? (const char*)g.A + (size_t)nxt.pm * tstepA : cA; const char* nB = has_next ? (const char*)g.Bt + (size_t)nxt.pn * tstepB : cB;
;         int t0 = 0;
;         if constexpr (SP2 && GEMM_RELAX == 1) { if (ui > 0) {
;             const char* a1 = cA + kstepA; const char* a2 = cA + 2 * kstepA; const char* b2 = cB + 2 * kstepB; const char* a3 = a2 + kstepA; const char* b3 = b2 + kstepB;
;             PG8_LDB(B0, 0, 0); PG8_LDB(B1, 0, 1); PG8_SCHED; PG8_LDA(At, 0, 0); PG8_STAGEA(PG8_SA(1, 1), a1 + hstepA, voffA);
;             PG8_WAIT_V(24); PG8_WAIT_L(0); PG8_BAR; PG8_MMA(0, 0, At, B0); PG8_MMA(0, 1, At, B1); PG8_BAR; PG8_SCHED;
;             PG8_LDA(At, 0, 1); PG8_STAGEB(PG8_SB(0, 0), b2, voffB); PG8_STAGEB(PG8_SB(0, 1), b2 + hstepB, voffB); PG8_STAGEA(PG8_SA(0, 0), a2, voffA);
;             PG8_WAIT_V(24); PG8_WAIT_L(0); PG8_BAR; PG8_MMA(1, 0, At, B0); PG8_MMA(1, 1, At, B1); PG8_BAR; PG8_SCHED;
;             PG8_LDB(B0, 1, 0); PG8_LDB(B1, 1, 1); PG8_SCHED; PG8_LDA(At, 1, 0); PG8_STAGEA(PG8_SA(0, 1), a2 + hstepA, voffA);
;             PG8_WAIT_V(8); PG8_WAIT_L(0); PG8_BAR; PG8_MMA(0, 0, At, B0); PG8_MMA(0, 1, At, B1); PG8_BAR; PG8_SCHED;
;             PG8_LDA(At, 1, 1); PG8_STAGEB(PG8_SB(1, 0), b3, voffB); PG8_STAGEB(PG8_SB(1, 1), b3 + hstepB, voffB); PG8_STAGEA(PG8_SA(1, 0), a3, voffA);
;             PG8_WAIT_V(8); PG8_WAIT_L(0); PG8_BAR; PG8_MMA(1, 0, At, B0); PG8_MMA(1, 1, At, B1); PG8_BAR; PG8_SCHED;
;             t0 = 2; } }
;     ...
;         asm volatile(".p2align " PG8_STR(GEMM_LOOP_ALIGN) ::: "memory");
;     ...
;         for (int t = t0; t < nt; t += 2) {
;             const bool last = (t == nt - 2);
;             const char* a1 = cA + (size_t)(t + 1) * kstepA;
;             const char* a2 = last ? nA : cA + (size_t)(t + 2) * kstepA; const char* b2 = last ? nB : cB + (size_t)(t + 2) * kstepB;
;             const char* a3 = a2 + kstepA; const char* b3 = b2 + kstepB;
;             if (last && has_next) S.a_ready(nxt);
;             if constexpr (SP2) {
;             PG8_LDB(B0, 0, 0); PG8_LDB(B1, 0, 1); PG8_SCHED; PG8_LDA(At, 0, 0); PG8_STAGEA(PG8_SA(1, 1), a1 + hstepA, voffA);
;     ...
;             const int relax = __builtin_amdgcn_readfirstlane((t == 0 && ui > 0) ? 1 : 0);
.LBB0_711:
	s_ashr_i32 s25, s24, 31
	s_lshl_b64 s[0:1], s[24:25], 21
	s_add_u32 s26, s56, s0
	s_addc_u32 s27, s57, s1
	s_and_b64 s[0:1], s[10:11], exec
	s_cselect_b32 s0, s27, s13
	s_cselect_b32 s1, s26, s12
	s_ashr_i32 s23, s22, 31
	s_lshl_b64 s[6:7], s[22:23], 21
	s_add_u32 s36, s51, s6
	s_addc_u32 s37, s68, s7
	s_and_b64 s[6:7], s[10:11], exec
	s_cselect_b32 s23, s37, s43
	s_cselect_b32 s25, s36, s42
	s_add_u32 s40, s12, 0x100080
	s_addc_u32 s41, s13, 0
	s_add_u32 s12, s42, 0x100
	s_addc_u32 s13, s43, 0
	s_mov_b32 s39, -2
	s_add_u32 s6, s40, 0xfff00080
	s_addc_u32 s7, s41, -1
	s_add_i32 s95, 0, 0x10000
	s_cmp_eq_u32 s39, 60
	s_cselect_b32 s43, s0, s7
	s_cselect_b32 s42, s1, s6
	v_add_u32_e32 v144, s95, v146
	s_cselect_b32 s17, s23, s13
	s_cselect_b32 s16, s25, s12
	s_add_i32 vcc_lo, 0, 0x14000
	ds_read_b128 v[150:153], v144
	ds_read_b128 v[154:157], v144 offset:1024
	ds_read_b128 v[158:161], v144 offset:2048
	ds_read_b128 v[162:165], v144 offset:3072
	v_add_u32_e32 v144, vcc_lo, v146
	ds_read_b128 v[166:169], v144
	ds_read_b128 v[170:173], v144 offset:1024
	ds_read_b128 v[174:177], v144 offset:2048
	ds_read_b128 v[178:181], v144 offset:3072
	v_lshl_add_u64 v[144:145], s[40:41], 0, v[140:141]
	s_add_i32 m0, s69, 0xc000
	ds_read_b128 v[182:185], v148
	ds_read_b128 v[186:189], v148 offset:1024
	ds_read_b128 v[190:193], v148 offset:2048
	ds_read_b128 v[194:197], v148 offset:3072
	ds_read_b128 v[198:201], v148 offset:4096
	ds_read_b128 v[202:205], v148 offset:5120
	ds_read_b128 v[206:209], v148 offset:6144
	ds_read_b128 v[210:213], v148 offset:7168
	global_load_lds_dwordx4 v[144:145], off
	v_lshl_add_u64 v[144:145], s[40:41], 0, v[142:143]
	s_add_i32 m0, s69, 0xe000
	s_nop 0
	global_load_lds_dwordx4 v[144:145], off
	s_waitcnt vmcnt(8)
	s_waitcnt lgkmcnt(0)
	s_nop 0
	s_setprio 1
	s_barrier
	v_mfma_f32_16x16x32_bf16 v[126:129], v[150:153], v[182:185], 0
	v_mfma_f32_16x16x32_bf16 v[122:125], v[158:161], v[182:185], 0
	v_mfma_f32_16x16x32_bf16 v[110:113], v[150:153], v[190:193], 0
	v_mfma_f32_16x16x32_bf16 v[106:109], v[158:161], v[190:193], 0
	v_mfma_f32_16x16x32_bf16 v[94:97], v[150:153], v[198:201], 0
	v_mfma_f32_16x16x32_bf16 v[90:93], v[158:161], v[198:201], 0
	v_mfma_f32_16x16x32_bf16 v[78:81], v[150:153], v[206:209], 0
	v_mfma_f32_16x16x32_bf16 v[74:77], v[158:161], v[206:209], 0
	v_mfma_f32_16x16x32_bf16 v[126:129], v[154:157], v[186:189], v[126:129]
	v_mfma_f32_16x16x32_bf16 v[122:125], v[162:165], v[186:189], v[122:125]
	v_mfma_f32_16x16x32_bf16 v[110:113], v[154:157], v[194:197], v[110:113]
	v_mfma_f32_16x16x32_bf16 v[106:109], v[162:165], v[194:197], v[106:109]
	v_mfma_f32_16x16x32_bf16 v[94:97], v[154:157], v[202:205], v[94:97]
	v_mfma_f32_16x16x32_bf16 v[90:93], v[162:165], v[202:205], v[90:93]
	v_mfma_f32_16x16x32_bf16 v[78:81], v[154:157], v[210:213], v[78:81]
	v_mfma_f32_16x16x32_bf16 v[74:77], v[162:165], v[210:213], v[74:77]
	v_mfma_f32_16x16x32_bf16 v[118:121], v[166:169], v[182:185], 0
	v_mfma_f32_16x16x32_bf16 v[114:117], v[174:177], v[182:185], 0
	v_mfma_f32_16x16x32_bf16 v[102:105], v[166:169], v[190:193], 0
	v_mfma_f32_16x16x32_bf16 v[98:101], v[174:177], v[190:193], 0
	v_mfma_f32_16x16x32_bf16 v[86:89], v[166:169], v[198:201], 0
	v_mfma_f32_16x16x32_bf16 v[82:85], v[174:177], v[198:201], 0
	v_mfma_f32_16x16x32_bf16 v[70:73], v[166:169], v[206:209], 0
	v_mfma_f32_16x16x32_bf16 v[66:69], v[174:177], v[206:209], 0
	v_mfma_f32_16x16x32_bf16 v[118:121], v[170:173], v[186:189], v[118:121]
	v_mfma_f32_16x16x32_bf16 v[114:117], v[178:181], v[186:189], v[114:117]
	v_mfma_f32_16x16x32_bf16 v[102:105], v[170:173], v[194:197], v[102:105]
	v_mfma_f32_16x16x32_bf16 v[98:101], v[178:181], v[194:197], v[98:101]
	v_mfma_f32_16x16x32_bf16 v[86:89], v[170:173], v[202:205], v[86:89]
	v_mfma_f32_16x16x32_bf16 v[82:85], v[178:181], v[202:205], v[82:85]
	v_mfma_f32_16x16x32_bf16 v[70:73], v[170:173], v[210:213], v[70:73]
	v_mfma_f32_16x16x32_bf16 v[66:69], v[178:181], v[210:213], v[66:69]
	s_barrier
	s_setprio 0
	s_add_i32 s6, s95, s50
	v_lshl_add_u64 v[144:145], s[16:17], 0, v[134:135]
	s_mov_b32 m0, s6
	ds_read_b128 v[182:185], v148 offset:16384
	ds_read_b128 v[186:189], v148 offset:17408
	ds_read_b128 v[190:193], v148 offset:18432
	ds_read_b128 v[194:197], v148 offset:19456
	ds_read_b128 v[198:201], v148 offset:20480
	ds_read_b128 v[202:205], v148 offset:21504
	ds_read_b128 v[206:209], v148 offset:22528
	ds_read_b128 v[210:213], v148 offset:23552
	global_load_lds_dwordx4 v[144:145], off
	s_add_i32 m0, s6, 0x2000
	s_add_u32 s6, s16, 0x100000
	v_lshl_add_u64 v[214:215], s[16:17], 0, v[130:131]
	s_addc_u32 s7, s17, 0
	s_add_i32 s95, vcc_lo, s50
	global_load_lds_dwordx4 v[214:215], off
	v_lshl_add_u64 v[216:217], s[6:7], 0, v[134:135]
	s_mov_b32 m0, s95
	v_lshl_add_u64 v[218:219], s[42:43], 0, v[132:133]
	global_load_lds_dwordx4 v[216:217], off
	v_lshl_add_u64 v[216:217], s[6:7], 0, v[130:131]
	s_add_i32 m0, s95, 0x2000
	s_nop 0
	global_load_lds_dwordx4 v[216:217], off
	v_lshl_add_u64 v[216:217], s[42:43], 0, v[136:137]
	s_mov_b32 m0, s69
	s_nop 0
	global_load_lds_dwordx4 v[216:217], off
	s_mov_b32 m0, s72
	s_nop 0
	global_load_lds_dwordx4 v[218:219], off
	s_waitcnt vmcnt(8)
	s_waitcnt lgkmcnt(0)
	s_setprio 1
	s_barrier
; #define PG8_STAGEA(bufoff, gbase, voff) PG8_STAGE_X(bufoff, gbase, voff, AUXA)
; #define PG8_LDA(dst, b, h) do { _Pragma("unroll") for (int m = 0; m < 4; ++m) _Pragma("unroll") for (int k = 0; k < 2; ++k) dst[m][k] = *(const PG8_LAS bf16x8*)(lds + PG8_SA(b, h) + aoff + m * 2048 + k * 1024); } while (0)
; #define PG8_LDB(dst, b, h) do { _Pragma("unroll") for (int n = 0; n < 2; ++n) _Pragma("unroll") for (int k = 0; k < 2; ++k) dst[n][k] = *(const PG8_LAS bf16x8*)(lds + PG8_SB(b, h) + boff + n * 2048 + k * 1024); } while (0)
; #define PG8_MMA(ai, bj, At, Bt) do { if (GEMM_PRIO_MODE == 0) __builtin_amdgcn_s_setprio(1); PG8_MMA_LOOPS \
;         acc[ai][bj][m][n] = __builtin_amdgcn_mfma_f32_16x16x32_bf16(Bt[n][k], At[m][k], acc[ai][bj][m][n], 0, 0, 0); if (GEMM_PRIO_MODE == 0) __builtin_amdgcn_s_setprio(0); } while (0)
; #define PG8_WAIT_V(n) asm volatile("s_waitcnt vmcnt(" #n ")" ::: "memory")
; #define PG8_WAIT_L(n) asm volatile("s_waitcnt lgkmcnt(" #n ")" ::: "memory")
; #define PG8_BAR __builtin_amdgcn_s_barrier()
; #define PG8_SCHED __builtin_amdgcn_sched_barrier(0)
;     ...
;             PG8_WAIT_V(8); PG8_WAIT_L(0); PG8_BAR; PG8_MMA(1, 0, At, B0); PG8_MMA(1, 1, At, B1); PG8_BAR; PG8_SCHED;
;     ...
;             PG8_LDB(B0, 1, 0); PG8_LDB(B1, 1, 1); PG8_SCHED; PG8_LDA(At, 1, 0); PG8_STAGEA(PG8_SA(0, 1), a2 + hstepA, voffA);
;             PG8_WAIT_V(8); PG8_WAIT_L(0); PG8_BAR; PG8_MMA(0, 0, At, B0); PG8_MMA(0, 1, At, B1); PG8_BAR; PG8_SCHED;
	v_mfma_f32_16x16x32_bf16 v[62:65], v[150:153], v[182:185], 0
	v_mfma_f32_16x16x32_bf16 v[58:61], v[158:161], v[182:185], 0
	v_mfma_f32_16x16x32_bf16 v[46:49], v[150:153], v[190:193], 0
	v_mfma_f32_16x16x32_bf16 v[42:45], v[158:161], v[190:193], 0
	v_mfma_f32_16x16x32_bf16 v[30:33], v[150:153], v[198:201], 0
	v_mfma_f32_16x16x32_bf16 v[26:29], v[158:161], v[198:201], 0
	v_mfma_f32_16x16x32_bf16 v[12:15], v[150:153], v[206:209], 0
	v_mfma_f32_16x16x32_bf16 v[8:11], v[158:161], v[206:209], 0
	v_mfma_f32_16x16x32_bf16 v[62:65], v[154:157], v[186:189], v[62:65]
	v_mfma_f32_16x16x32_bf16 v[58:61], v[162:165], v[186:189], v[58:61]
	v_mfma_f32_16x16x32_bf16 v[46:49], v[154:157], v[194:197], v[46:49]
	v_mfma_f32_16x16x32_bf16 v[42:45], v[162:165], v[194:197], v[42:45]
	v_mfma_f32_16x16x32_bf16 v[30:33], v[154:157], v[202:205], v[30:33]
	v_mfma_f32_16x16x32_bf16 v[26:29], v[162:165], v[202:205], v[26:29]
	v_mfma_f32_16x16x32_bf16 v[12:15], v[154:157], v[210:213], v[12:15]
	v_mfma_f32_16x16x32_bf16 v[8:11], v[162:165], v[210:213], v[8:11]
	v_mfma_f32_16x16x32_bf16 v[54:57], v[166:169], v[182:185], 0
	v_mfma_f32_16x16x32_bf16 v[50:53], v[174:177], v[182:185], 0
	v_mfma_f32_16x16x32_bf16 v[38:41], v[166:169], v[190:193], 0
	v_mfma_f32_16x16x32_bf16 v[34:37], v[174:177], v[190:193], 0
	v_mfma_f32_16x16x32_bf16 v[22:25], v[166:169], v[198:201], 0
	v_mfma_f32_16x16x32_bf16 v[18:21], v[174:177], v[198:201], 0
	v_mfma_f32_16x16x32_bf16 v[4:7], v[166:169], v[206:209], 0
	v_mfma_f32_16x16x32_bf16 v[0:3], v[174:177], v[206:209], 0
	v_mfma_f32_16x16x32_bf16 v[54:57], v[170:173], v[186:189], v[54:57]
	v_mfma_f32_16x16x32_bf16 v[50:53], v[178:181], v[186:189], v[50:53]
	v_mfma_f32_16x16x32_bf16 v[38:41], v[170:173], v[194:197], v[38:41]
	v_mfma_f32_16x16x32_bf16 v[34:37], v[178:181], v[194:197], v[34:37]
	v_mfma_f32_16x16x32_bf16 v[22:25], v[170:173], v[202:205], v[22:25]
	v_mfma_f32_16x16x32_bf16 v[18:21], v[178:181], v[202:205], v[18:21]
	v_mfma_f32_16x16x32_bf16 v[4:7], v[170:173], v[210:213], v[4:7]
	v_mfma_f32_16x16x32_bf16 v[0:3], v[178:181], v[210:213], v[0:3]
	s_barrier
	s_setprio 0
	s_add_i32 s95, 0, 0x18000
	v_add_u32_e32 v149, s95, v146
	s_add_i32 vcc_lo, 0, 0x1c000
	ds_read_b128 v[150:153], v149
	ds_read_b128 v[154:157], v149 offset:1024
	ds_read_b128 v[158:161], v149 offset:2048
	ds_read_b128 v[162:165], v149 offset:3072
	v_add_u32_e32 v149, vcc_lo, v146
	ds_read_b128 v[166:169], v149
	ds_read_b128 v[170:173], v149 offset:1024
	ds_read_b128 v[174:177], v149 offset:2048
	ds_read_b128 v[178:181], v149 offset:3072
	s_add_u32 s6, s42, 0x100000
	s_addc_u32 s7, s43, 0
	s_mov_b32 m0, s73
	v_lshl_add_u64 v[220:221], s[6:7], 0, v[136:137]
	ds_read_b128 v[182:185], v148 offset:32768
	ds_read_b128 v[186:189], v148 offset:33792
	ds_read_b128 v[190:193], v148 offset:34816
	ds_read_b128 v[194:197], v148 offset:35840
	ds_read_b128 v[198:201], v148 offset:36864
	ds_read_b128 v[202:205], v148 offset:37888
	ds_read_b128 v[206:209], v148 offset:38912
	ds_read_b128 v[210:213], v148 offset:39936
	global_load_lds_dwordx4 v[220:221], off
	v_lshl_add_u64 v[220:221], s[6:7], 0, v[132:133]
	s_mov_b32 m0, s82
	s_nop 0
	global_load_lds_dwordx4 v[220:221], off
	s_waitcnt vmcnt(8)
	s_waitcnt lgkmcnt(0)
	s_nop 0
	s_nop 0
	s_setprio 1
	s_barrier
	v_mfma_f32_16x16x32_bf16 v[126:129], v[150:153], v[182:185], v[126:129]
	v_mfma_f32_16x16x32_bf16 v[122:125], v[158:161], v[182:185], v[122:125]
	v_mfma_f32_16x16x32_bf16 v[110:113], v[150:153], v[190:193], v[110:113]
	v_mfma_f32_16x16x32_bf16 v[106:109], v[158:161], v[190:193], v[106:109]
	v_mfma_f32_16x16x32_bf16 v[94:97], v[150:153], v[198:201], v[94:97]
	v_mfma_f32_16x16x32_bf16 v[90:93], v[158:161], v[198:201], v[90:93]
	v_mfma_f32_16x16x32_bf16 v[78:81], v[150:153], v[206:209], v[78:81]
	v_mfma_f32_16x16x32_bf16 v[74:77], v[158:161], v[206:209], v[74:77]
	v_mfma_f32_16x16x32_bf16 v[126:129], v[154:157], v[186:189], v[126:129]
	v_mfma_f32_16x16x32_bf16 v[122:125], v[162:165], v[186:189], v[122:125]
	v_mfma_f32_16x16x32_bf16 v[110:113], v[154:157], v[194:197], v[110:113]
	v_mfma_f32_16x16x32_bf16 v[106:109], v[162:165], v[194:197], v[106:109]
	v_mfma_f32_16x16x32_bf16 v[94:97], v[154:157], v[202:205], v[94:97]
	v_mfma_f32_16x16x32_bf16 v[90:93], v[162:165], v[202:205], v[90:93]
	v_mfma_f32_16x16x32_bf16 v[78:81], v[154:157], v[210:213], v[78:81]
	v_mfma_f32_16x16x32_bf16 v[74:77], v[162:165], v[210:213], v[74:77]
	v_mfma_f32_16x16x32_bf16 v[118:121], v[166:169], v[182:185], v[118:121]
	v_mfma_f32_16x16x32_bf16 v[114:117], v[174:177], v[182:185], v[114:117]
	v_mfma_f32_16x16x32_bf16 v[102:105], v[166:169], v[190:193], v[102:105]
	v_mfma_f32_16x16x32_bf16 v[98:101], v[174:177], v[190:193], v[98:101]
	v_mfma_f32_16x16x32_bf16 v[86:89], v[166:169], v[198:201], v[86:89]
	v_mfma_f32_16x16x32_bf16 v[82:85], v[174:177], v[198:201], v[82:85]
	v_mfma_f32_16x16x32_bf16 v[70:73], v[166:169], v[206:209], v[70:73]
	v_mfma_f32_16x16x32_bf16 v[66:69], v[174:177], v[206:209], v[66:69]
	v_mfma_f32_16x16x32_bf16 v[118:121], v[170:173], v[186:189], v[118:121]
	v_mfma_f32_16x16x32_bf16 v[114:117], v[178:181], v[186:189], v[114:117]
	v_mfma_f32_16x16x32_bf16 v[102:105], v[170:173], v[194:197], v[102:105]
	v_mfma_f32_16x16x32_bf16 v[98:101], v[178:181], v[194:197], v[98:101]
	v_mfma_f32_16x16x32_bf16 v[86:89], v[170:173], v[202:205], v[86:89]
	v_mfma_f32_16x16x32_bf16 v[82:85], v[178:181], v[202:205], v[82:85]
	v_mfma_f32_16x16x32_bf16 v[70:73], v[170:173], v[210:213], v[70:73]
	v_mfma_f32_16x16x32_bf16 v[66:69], v[178:181], v[210:213], v[66:69]
	s_barrier
; #define PG8_STAGEA(bufoff, gbase, voff) PG8_STAGE_X(bufoff, gbase, voff, AUXA)
; #define PG8_STAGEB(bufoff, gbase, voff) PG8_STAGE_X(bufoff, gbase, voff, AUXB)
; #define PG8_LDA(dst, b, h) do { _Pragma("unroll") for (int m = 0; m < 4; ++m) _Pragma("unroll") for (int k = 0; k < 2; ++k) dst[m][k] = *(const PG8_LAS bf16x8*)(lds + PG8_SA(b, h) + aoff + m * 2048 + k * 1024); } while (0)
; #define PG8_MMA(ai, bj, At, Bt) do { if (GEMM_PRIO_MODE == 0) __builtin_amdgcn_s_setprio(1); PG8_MMA_LOOPS \
;         acc[ai][bj][m][n] = __builtin_amdgcn_mfma_f32_16x16x32_bf16(Bt[n][k], At[m][k], acc[ai][bj][m][n], 0, 0, 0); if (GEMM_PRIO_MODE == 0) __builtin_amdgcn_s_setprio(0); } while (0)
; #define PG8_WAIT_V(n) asm volatile("s_waitcnt vmcnt(" #n ")" ::: "memory")
; #define PG8_WAIT_L(n) asm volatile("s_waitcnt lgkmcnt(" #n ")" ::: "memory")
; #define PG8_BAR __builtin_amdgcn_s_barrier()
; #define PG8_SCHED __builtin_amdgcn_sched_barrier(0)
;     ...
;             PG8_LDA(At, 1, 1); PG8_STAGEB(PG8_SB(1, 0), b3, voffB); PG8_STAGEB(PG8_SB(1, 1), b3 + hstepB, voffB); PG8_STAGEA(PG8_SA(1, 0), a3, voffA);
;             PG8_WAIT_V(8); PG8_WAIT_L(0); PG8_BAR; PG8_MMA(1, 0, At, B0); PG8_MMA(1, 1, At, B1); PG8_BAR; PG8_SCHED;
	s_setprio 0
	s_add_i32 s6, s95, s50
	v_lshl_add_u64 v[144:145], v[144:145], 0, s[86:87]
	s_mov_b32 m0, s6
	ds_read_b128 v[182:185], v148 offset:49152
	ds_read_b128 v[186:189], v148 offset:50176
	ds_read_b128 v[190:193], v148 offset:51200
	ds_read_b128 v[194:197], v148 offset:52224
	ds_read_b128 v[198:201], v148 offset:53248
	ds_read_b128 v[202:205], v148 offset:54272
	ds_read_b128 v[206:209], v148 offset:55296
	ds_read_b128 v[210:213], v148 offset:56320
	global_load_lds_dwordx4 v[144:145], off
	s_add_i32 m0, s6, 0x2000
	s_add_u32 s6, s16, 0x100080
	v_lshl_add_u64 v[144:145], v[214:215], 0, s[86:87]
	s_addc_u32 s7, s17, 0
	s_add_i32 s16, vcc_lo, s50
	global_load_lds_dwordx4 v[144:145], off
	v_lshl_add_u64 v[144:145], s[6:7], 0, v[134:135]
	s_mov_b32 m0, s16
	s_nop 0
	global_load_lds_dwordx4 v[144:145], off
	v_lshl_add_u64 v[144:145], s[6:7], 0, v[130:131]
	s_add_i32 m0, s16, 0x2000
	s_nop 0
	global_load_lds_dwordx4 v[144:145], off
	v_lshl_add_u64 v[144:145], v[216:217], 0, s[86:87]
	s_mov_b32 m0, s83
	s_nop 0
	global_load_lds_dwordx4 v[144:145], off
	v_lshl_add_u64 v[144:145], v[218:219], 0, s[86:87]
	s_mov_b32 m0, s90
	s_nop 0
	global_load_lds_dwordx4 v[144:145], off
	s_waitcnt vmcnt(8)
	s_waitcnt lgkmcnt(0)
	s_nop 0
	s_setprio 1
	s_barrier
	v_mfma_f32_16x16x32_bf16 v[62:65], v[150:153], v[182:185], v[62:65]
	v_mfma_f32_16x16x32_bf16 v[58:61], v[158:161], v[182:185], v[58:61]
	v_mfma_f32_16x16x32_bf16 v[46:49], v[150:153], v[190:193], v[46:49]
	v_mfma_f32_16x16x32_bf16 v[42:45], v[158:161], v[190:193], v[42:45]
	v_mfma_f32_16x16x32_bf16 v[30:33], v[150:153], v[198:201], v[30:33]
	v_mfma_f32_16x16x32_bf16 v[26:29], v[158:161], v[198:201], v[26:29]
	v_mfma_f32_16x16x32_bf16 v[12:15], v[150:153], v[206:209], v[12:15]
	v_mfma_f32_16x16x32_bf16 v[8:11], v[158:161], v[206:209], v[8:11]
	v_mfma_f32_16x16x32_bf16 v[62:65], v[154:157], v[186:189], v[62:65]
	v_mfma_f32_16x16x32_bf16 v[58:61], v[162:165], v[186:189], v[58:61]
	v_mfma_f32_16x16x32_bf16 v[46:49], v[154:157], v[194:197], v[46:49]
	v_mfma_f32_16x16x32_bf16 v[42:45], v[162:165], v[194:197], v[42:45]
	v_mfma_f32_16x16x32_bf16 v[30:33], v[154:157], v[202:205], v[30:33]
	v_mfma_f32_16x16x32_bf16 v[26:29], v[162:165], v[202:205], v[26:29]
	v_mfma_f32_16x16x32_bf16 v[12:15], v[154:157], v[210:213], v[12:15]
	v_mfma_f32_16x16x32_bf16 v[8:11], v[162:165], v[210:213], v[8:11]
	v_mfma_f32_16x16x32_bf16 v[54:57], v[166:169], v[182:185], v[54:57]
	v_mfma_f32_16x16x32_bf16 v[50:53], v[174:177], v[182:185], v[50:53]
	v_mfma_f32_16x16x32_bf16 v[38:41], v[166:169], v[190:193], v[38:41]
	v_mfma_f32_16x16x32_bf16 v[34:37], v[174:177], v[190:193], v[34:37]
	v_mfma_f32_16x16x32_bf16 v[22:25], v[166:169], v[198:201], v[22:25]
	v_mfma_f32_16x16x32_bf16 v[18:21], v[174:177], v[198:201], v[18:21]
	v_mfma_f32_16x16x32_bf16 v[4:7], v[166:169], v[206:209], v[4:7]
	v_mfma_f32_16x16x32_bf16 v[0:3], v[174:177], v[206:209], v[0:3]
	v_mfma_f32_16x16x32_bf16 v[54:57], v[170:173], v[186:189], v[54:57]
	v_mfma_f32_16x16x32_bf16 v[50:53], v[178:181], v[186:189], v[50:53]
	v_mfma_f32_16x16x32_bf16 v[38:41], v[170:173], v[194:197], v[38:41]
	v_mfma_f32_16x16x32_bf16 v[34:37], v[178:181], v[194:197], v[34:37]
	v_mfma_f32_16x16x32_bf16 v[22:25], v[170:173], v[202:205], v[22:25]
	v_mfma_f32_16x16x32_bf16 v[18:21], v[178:181], v[202:205], v[18:21]
	v_mfma_f32_16x16x32_bf16 v[4:7], v[170:173], v[210:213], v[4:7]
	v_mfma_f32_16x16x32_bf16 v[0:3], v[178:181], v[210:213], v[0:3]
	s_barrier
	s_setprio 0
	s_add_i32 s39, s39, 2
	s_add_u32 s40, s40, 0x100
	s_addc_u32 s41, s41, 0
	s_add_u32 s12, s12, 0x100
	s_addc_u32 s13, s13, 0

; #define PG8_STAGEA(bufoff, gbase, voff) PG8_STAGE_X(bufoff, gbase, voff, AUXA)
; #define PG8_STAGEB(bufoff, gbase, voff) PG8_STAGE_X(bufoff, gbase, voff, AUXB)
; #define PG8_LDA(dst, b, h) do { _Pragma("unroll") for (int m = 0; m < 4; ++m) _Pragma("unroll") for (int k = 0; k < 2; ++k) dst[m][k] = *(const PG8_LAS bf16x8*)(lds + PG8_SA(b, h) + aoff + m * 2048 + k * 1024); } while (0)
; #define PG8_LDB(dst, b, h) do { _Pragma("unroll") for (int n = 0; n < 2; ++n) _Pragma("unroll") for (int k = 0; k < 2; ++k) dst[n][k] = *(const PG8_LAS bf16x8*)(lds + PG8_SB(b, h) + boff + n * 2048 + k * 1024); } while (0)
; #define PG8_MMA(ai, bj, At, Bt) do { if (GEMM_PRIO_MODE == 0) __builtin_amdgcn_s_setprio(1); PG8_MMA_LOOPS \
;         acc[ai][bj][m][n] = __builtin_amdgcn_mfma_f32_16x16x32_bf16(Bt[n][k], At[m][k], acc[ai][bj][m][n], 0, 0, 0); if (GEMM_PRIO_MODE == 0) __builtin_amdgcn_s_setprio(0); } while (0)
; #define PG8_WAIT_V(n) asm volatile("s_waitcnt vmcnt(" #n ")" ::: "memory")
; #define PG8_WAIT_VR(n, nr, flag) asm volatile("s_cmp_eq_u32 %0, 0\n\ts_cbranch_scc1 .Lpg8s%=\n\ts_waitcnt vmcnt(" #nr ")\n\ts_branch .Lpg8d%=\n.Lpg8s%=:\n\ts_waitcnt vmcnt(" #n ")\n.Lpg8d%=:" :: "s"(flag) : "memory", "scc")
; #define PG8_WAIT_L(n) asm volatile("s_waitcnt lgkmcnt(" #n ")" ::: "memory")
; #define PG8_BAR __builtin_amdgcn_s_barrier()
;     ...
;             const bool last = (t == nt - 2);
;             const char* a1 = cA + (size_t)(t + 1) * kstepA;
;             const char* a2 = last ? nA : cA + (size_t)(t + 2) * kstepA; const char* b2 = last ? nB : cB + (size_t)(t + 2) * kstepB;
;             const char* a3 = a2 + kstepA; const char* b3 = b2 + kstepB;
;             if (last && has_next) S.a_ready(nxt);
;             if constexpr (SP2) {
;             PG8_LDB(B0, 0, 0); PG8_LDB(B1, 0, 1); PG8_SCHED; PG8_LDA(At, 0, 0); PG8_STAGEA(PG8_SA(1, 1), a1 + hstepA, voffA);
;     ...
;             const int relax = __builtin_amdgcn_readfirstlane((t == 0 && ui > 0) ? 1 : 0);
;             PG8_WAIT_VR(8, 24, relax); PG8_WAIT_L(0); PG8_BAR; PG8_MMA(0, 0, At, B0); PG8_MMA(0, 1, At, B1); PG8_BAR; PG8_SCHED;
;     ...
;             PG8_WAIT_V(8); PG8_WAIT_L(0); PG8_BAR; PG8_MMA(0, 0, At, B0); PG8_MMA(0, 1, At, B1); PG8_BAR; PG8_SCHED;
;     ...
;             PG8_LDA(At, 0, 1); PG8_STAGEB(PG8_SB(0, 0), b2, voffB); PG8_STAGEB(PG8_SB(0, 1), b2 + hstepB, voffB); PG8_STAGEA(PG8_SA(0, 0), a2, voffA);
.LBB0_848:
	s_add_u32 s16, s24, 0x4000
	s_addc_u32 s17, s25, 0
	s_cmpk_eq_i32 s82, 0xfc
	s_cselect_b32 s36, s73, s16
	s_cselect_b32 s37, s11, s17
	s_cselect_b32 s16, s78, s0
	s_cselect_b32 s17, s15, s1
	s_add_u32 s26, s36, 0x8000
	s_addc_u32 s27, s37, 0
	s_add_i32 s83, 0, 0x10000
	s_add_i32 s94, 0, 0x14000
	v_add_u32_e32 v152, s83, v157
	v_add_u32_e32 v174, s94, v157
	ds_read_b128 v[130:133], v152
	ds_read_b128 v[134:137], v152 offset:1024
	ds_read_b128 v[148:151], v152 offset:2048
	ds_read_b128 v[152:155], v152 offset:3072
	ds_read_b128 v[162:165], v174
	ds_read_b128 v[166:169], v174 offset:1024
	ds_read_b128 v[170:173], v174 offset:2048
	ds_read_b128 v[174:177], v174 offset:3072
	v_lshl_add_u64 v[210:211], s[24:25], 0, v[144:145]
	s_add_i32 m0, s39, 0xc000
	ds_read_b128 v[178:181], v161
	ds_read_b128 v[182:185], v161 offset:1024
	ds_read_b128 v[186:189], v161 offset:2048
	ds_read_b128 v[190:193], v161 offset:3072
	ds_read_b128 v[194:197], v161 offset:4096
	ds_read_b128 v[198:201], v161 offset:5120
	ds_read_b128 v[202:205], v161 offset:6144
	ds_read_b128 v[206:209], v161 offset:7168
	global_load_lds_dwordx4 v[210:211], off
	v_lshl_add_u64 v[210:211], s[24:25], 0, v[146:147]
	s_add_i32 m0, s39, 0xe000
	s_nop 0
	global_load_lds_dwordx4 v[210:211], off
	s_waitcnt vmcnt(8)
	s_waitcnt lgkmcnt(0)
	s_nop 0
	s_setprio 1
	s_barrier
	v_mfma_f32_16x16x32_bf16 v[126:129], v[130:133], v[178:181], v[126:129]
	v_mfma_f32_16x16x32_bf16 v[122:125], v[148:151], v[178:181], v[122:125]
	v_mfma_f32_16x16x32_bf16 v[110:113], v[130:133], v[186:189], v[110:113]
	v_mfma_f32_16x16x32_bf16 v[106:109], v[148:151], v[186:189], v[106:109]
	v_mfma_f32_16x16x32_bf16 v[94:97], v[130:133], v[194:197], v[94:97]
	v_mfma_f32_16x16x32_bf16 v[90:93], v[148:151], v[194:197], v[90:93]
	v_mfma_f32_16x16x32_bf16 v[78:81], v[130:133], v[202:205], v[78:81]
	v_mfma_f32_16x16x32_bf16 v[74:77], v[148:151], v[202:205], v[74:77]
	v_mfma_f32_16x16x32_bf16 v[126:129], v[134:137], v[182:185], v[126:129]
	v_mfma_f32_16x16x32_bf16 v[122:125], v[152:155], v[182:185], v[122:125]
	v_mfma_f32_16x16x32_bf16 v[110:113], v[134:137], v[190:193], v[110:113]
	v_mfma_f32_16x16x32_bf16 v[106:109], v[152:155], v[190:193], v[106:109]
	v_mfma_f32_16x16x32_bf16 v[94:97], v[134:137], v[198:201], v[94:97]
	v_mfma_f32_16x16x32_bf16 v[90:93], v[152:155], v[198:201], v[90:93]
	v_mfma_f32_16x16x32_bf16 v[78:81], v[134:137], v[206:209], v[78:81]
	v_mfma_f32_16x16x32_bf16 v[74:77], v[152:155], v[206:209], v[74:77]
	v_mfma_f32_16x16x32_bf16 v[118:121], v[162:165], v[178:181], v[118:121]
	v_mfma_f32_16x16x32_bf16 v[114:117], v[170:173], v[178:181], v[114:117]
	v_mfma_f32_16x16x32_bf16 v[102:105], v[162:165], v[186:189], v[102:105]
	v_mfma_f32_16x16x32_bf16 v[98:101], v[170:173], v[186:189], v[98:101]
	v_mfma_f32_16x16x32_bf16 v[86:89], v[162:165], v[194:197], v[86:89]
	v_mfma_f32_16x16x32_bf16 v[82:85], v[170:173], v[194:197], v[82:85]
	v_mfma_f32_16x16x32_bf16 v[70:73], v[162:165], v[202:205], v[70:73]
	v_mfma_f32_16x16x32_bf16 v[66:69], v[170:173], v[202:205], v[66:69]
	v_mfma_f32_16x16x32_bf16 v[118:121], v[166:169], v[182:185], v[118:121]
	v_mfma_f32_16x16x32_bf16 v[114:117], v[174:177], v[182:185], v[114:117]
	v_mfma_f32_16x16x32_bf16 v[102:105], v[166:169], v[190:193], v[102:105]
	v_mfma_f32_16x16x32_bf16 v[98:101], v[174:177], v[190:193], v[98:101]
	v_mfma_f32_16x16x32_bf16 v[86:89], v[166:169], v[198:201], v[86:89]
	v_mfma_f32_16x16x32_bf16 v[82:85], v[174:177], v[198:201], v[82:85]
	v_mfma_f32_16x16x32_bf16 v[70:73], v[166:169], v[206:209], v[70:73]
	v_mfma_f32_16x16x32_bf16 v[66:69], v[174:177], v[206:209], v[66:69]
	s_barrier
	s_setprio 0
	s_add_i32 s83, s83, s38
	v_lshl_add_u64 v[210:211], s[16:17], 0, v[16:17]
	s_mov_b32 m0, s83
	ds_read_b128 v[178:181], v161 offset:16384
	ds_read_b128 v[182:185], v161 offset:17408
	ds_read_b128 v[186:189], v161 offset:18432
	ds_read_b128 v[190:193], v161 offset:19456
	ds_read_b128 v[194:197], v161 offset:20480
	ds_read_b128 v[198:201], v161 offset:21504
	ds_read_b128 v[202:205], v161 offset:22528
	ds_read_b128 v[206:209], v161 offset:23552
	global_load_lds_dwordx4 v[210:211], off
	s_add_i32 m0, s83, 0x2000
	s_add_u32 s90, s16, 0x4000
	v_lshl_add_u64 v[210:211], s[16:17], 0, v[138:139]
	s_addc_u32 s91, s17, 0
	s_add_i32 s83, s94, s38
	global_load_lds_dwordx4 v[210:211], off
	v_lshl_add_u64 v[210:211], s[90:91], 0, v[16:17]
	s_mov_b32 m0, s83
	s_nop 0
	global_load_lds_dwordx4 v[210:211], off
	v_lshl_add_u64 v[210:211], s[90:91], 0, v[138:139]
	s_add_i32 m0, s83, 0x2000
	s_nop 0
	global_load_lds_dwordx4 v[210:211], off
	v_lshl_add_u64 v[210:211], s[36:37], 0, v[142:143]
	s_mov_b32 m0, s39
	s_nop 0
	global_load_lds_dwordx4 v[210:211], off
	v_lshl_add_u64 v[210:211], s[36:37], 0, v[140:141]
	s_mov_b32 m0, s40
	s_nop 0
	global_load_lds_dwordx4 v[210:211], off
	s_waitcnt vmcnt(8)
	s_waitcnt lgkmcnt(0)
	s_nop 0
	s_setprio 1
	s_barrier
; #define PG8_STAGEA(bufoff, gbase, voff) PG8_STAGE_X(bufoff, gbase, voff, AUXA)
; #define PG8_STAGEB(bufoff, gbase, voff) PG8_STAGE_X(bufoff, gbase, voff, AUXB)
; #define PG8_LDA(dst, b, h) do { _Pragma("unroll") for (int m = 0; m < 4; ++m) _Pragma("unroll") for (int k = 0; k < 2; ++k) dst[m][k] = *(const PG8_LAS bf16x8*)(lds + PG8_SA(b, h) + aoff + m * 2048 + k * 1024); } while (0)
; #define PG8_LDB(dst, b, h) do { _Pragma("unroll") for (int n = 0; n < 2; ++n) _Pragma("unroll") for (int k = 0; k < 2; ++k) dst[n][k] = *(const PG8_LAS bf16x8*)(lds + PG8_SB(b, h) + boff + n * 2048 + k * 1024); } while (0)
; #define PG8_MMA(ai, bj, At, Bt) do { if (GEMM_PRIO_MODE == 0) __builtin_amdgcn_s_setprio(1); PG8_MMA_LOOPS \
;         acc[ai][bj][m][n] = __builtin_amdgcn_mfma_f32_16x16x32_bf16(Bt[n][k], At[m][k], acc[ai][bj][m][n], 0, 0, 0); if (GEMM_PRIO_MODE == 0) __builtin_amdgcn_s_setprio(0); } while (0)
; #define PG8_WAIT_V(n) asm volatile("s_waitcnt vmcnt(" #n ")" ::: "memory")
; #define PG8_WAIT_VR(n, nr, flag) asm volatile("s_cmp_eq_u32 %0, 0\n\ts_cbranch_scc1 .Lpg8s%=\n\ts_waitcnt vmcnt(" #nr ")\n\ts_branch .Lpg8d%=\n.Lpg8s%=:\n\ts_waitcnt vmcnt(" #n ")\n.Lpg8d%=:" :: "s"(flag) : "memory", "scc")
; #define PG8_WAIT_L(n) asm volatile("s_waitcnt lgkmcnt(" #n ")" ::: "memory")
; #define PG8_BAR __builtin_amdgcn_s_barrier()
; #define PG8_SCHED __builtin_amdgcn_sched_barrier(0)
;     ...
;             PG8_LDA(At, 0, 1); PG8_STAGEB(PG8_SB(0, 0), b2, voffB); PG8_STAGEB(PG8_SB(0, 1), b2 + hstepB, voffB); PG8_STAGEA(PG8_SA(0, 0), a2, voffA);
;     ...
;             PG8_WAIT_VR(8, 24, relax); PG8_WAIT_L(0); PG8_BAR; PG8_MMA(1, 0, At, B0); PG8_MMA(1, 1, At, B1); PG8_BAR; PG8_SCHED;
;     ...
;             PG8_WAIT_V(8); PG8_WAIT_L(0); PG8_BAR; PG8_MMA(1, 0, At, B0); PG8_MMA(1, 1, At, B1); PG8_BAR; PG8_SCHED;
;     ...
;             PG8_LDB(B0, 1, 0); PG8_LDB(B1, 1, 1); PG8_SCHED; PG8_LDA(At, 1, 0); PG8_STAGEA(PG8_SA(0, 1), a2 + hstepA, voffA);
;             PG8_WAIT_V(8); PG8_WAIT_L(0); PG8_BAR; PG8_MMA(0, 0, At, B0); PG8_MMA(0, 1, At, B1); PG8_BAR; PG8_SCHED;
	v_mfma_f32_16x16x32_bf16 v[62:65], v[130:133], v[178:181], v[62:65]
	v_mfma_f32_16x16x32_bf16 v[58:61], v[148:151], v[178:181], v[58:61]
	v_mfma_f32_16x16x32_bf16 v[46:49], v[130:133], v[186:189], v[46:49]
	v_mfma_f32_16x16x32_bf16 v[42:45], v[148:151], v[186:189], v[42:45]
	v_mfma_f32_16x16x32_bf16 v[30:33], v[130:133], v[194:197], v[30:33]
	v_mfma_f32_16x16x32_bf16 v[26:29], v[148:151], v[194:197], v[26:29]
	v_mfma_f32_16x16x32_bf16 v[12:15], v[130:133], v[202:205], v[12:15]
	v_mfma_f32_16x16x32_bf16 v[8:11], v[148:151], v[202:205], v[8:11]
	v_mfma_f32_16x16x32_bf16 v[62:65], v[134:137], v[182:185], v[62:65]
	v_mfma_f32_16x16x32_bf16 v[58:61], v[152:155], v[182:185], v[58:61]
	v_mfma_f32_16x16x32_bf16 v[46:49], v[134:137], v[190:193], v[46:49]
	v_mfma_f32_16x16x32_bf16 v[42:45], v[152:155], v[190:193], v[42:45]
	v_mfma_f32_16x16x32_bf16 v[30:33], v[134:137], v[198:201], v[30:33]
	v_mfma_f32_16x16x32_bf16 v[26:29], v[152:155], v[198:201], v[26:29]
	v_mfma_f32_16x16x32_bf16 v[12:15], v[134:137], v[206:209], v[12:15]
	v_mfma_f32_16x16x32_bf16 v[8:11], v[152:155], v[206:209], v[8:11]
	v_mfma_f32_16x16x32_bf16 v[54:57], v[162:165], v[178:181], v[54:57]
	v_mfma_f32_16x16x32_bf16 v[50:53], v[170:173], v[178:181], v[50:53]
	v_mfma_f32_16x16x32_bf16 v[38:41], v[162:165], v[186:189], v[38:41]
	v_mfma_f32_16x16x32_bf16 v[34:37], v[170:173], v[186:189], v[34:37]
	v_mfma_f32_16x16x32_bf16 v[22:25], v[162:165], v[194:197], v[22:25]
	v_mfma_f32_16x16x32_bf16 v[18:21], v[170:173], v[194:197], v[18:21]
	v_mfma_f32_16x16x32_bf16 v[4:7], v[162:165], v[202:205], v[4:7]
	v_mfma_f32_16x16x32_bf16 v[0:3], v[170:173], v[202:205], v[0:3]
	v_mfma_f32_16x16x32_bf16 v[54:57], v[166:169], v[182:185], v[54:57]
	v_mfma_f32_16x16x32_bf16 v[50:53], v[174:177], v[182:185], v[50:53]
	v_mfma_f32_16x16x32_bf16 v[38:41], v[166:169], v[190:193], v[38:41]
	v_mfma_f32_16x16x32_bf16 v[34:37], v[174:177], v[190:193], v[34:37]
	v_mfma_f32_16x16x32_bf16 v[22:25], v[166:169], v[198:201], v[22:25]
	v_mfma_f32_16x16x32_bf16 v[18:21], v[174:177], v[198:201], v[18:21]
	v_mfma_f32_16x16x32_bf16 v[4:7], v[166:169], v[206:209], v[4:7]
	v_mfma_f32_16x16x32_bf16 v[0:3], v[174:177], v[206:209], v[0:3]
	s_barrier
	s_setprio 0
	s_add_i32 s83, 0, 0x18000
	s_add_i32 s90, 0, 0x1c000
	v_add_u32_e32 v152, s83, v157
	v_add_u32_e32 v174, s90, v157
	ds_read_b128 v[130:133], v152
	ds_read_b128 v[134:137], v152 offset:1024
	ds_read_b128 v[148:151], v152 offset:2048
	ds_read_b128 v[152:155], v152 offset:3072
	ds_read_b128 v[162:165], v174
	ds_read_b128 v[166:169], v174 offset:1024
	ds_read_b128 v[170:173], v174 offset:2048
	ds_read_b128 v[174:177], v174 offset:3072
	s_add_u32 s36, s36, 0x4000
	s_addc_u32 s37, s37, 0
	s_mov_b32 m0, s41
	v_lshl_add_u64 v[210:211], s[36:37], 0, v[142:143]
	ds_read_b128 v[178:181], v161 offset:32768
	ds_read_b128 v[182:185], v161 offset:33792
	ds_read_b128 v[186:189], v161 offset:34816
	ds_read_b128 v[190:193], v161 offset:35840
	ds_read_b128 v[194:197], v161 offset:36864
	ds_read_b128 v[198:201], v161 offset:37888
	ds_read_b128 v[202:205], v161 offset:38912
	ds_read_b128 v[206:209], v161 offset:39936
	global_load_lds_dwordx4 v[210:211], off
	v_lshl_add_u64 v[210:211], s[36:37], 0, v[140:141]
	s_mov_b32 m0, s42
	s_nop 0
	global_load_lds_dwordx4 v[210:211], off
	s_waitcnt vmcnt(8)
	s_waitcnt lgkmcnt(0)
	s_setprio 1
	s_barrier
	v_mfma_f32_16x16x32_bf16 v[126:129], v[130:133], v[178:181], v[126:129]
	v_mfma_f32_16x16x32_bf16 v[122:125], v[148:151], v[178:181], v[122:125]
	v_mfma_f32_16x16x32_bf16 v[110:113], v[130:133], v[186:189], v[110:113]
	v_mfma_f32_16x16x32_bf16 v[106:109], v[148:151], v[186:189], v[106:109]
	v_mfma_f32_16x16x32_bf16 v[94:97], v[130:133], v[194:197], v[94:97]
	v_mfma_f32_16x16x32_bf16 v[90:93], v[148:151], v[194:197], v[90:93]
	v_mfma_f32_16x16x32_bf16 v[78:81], v[130:133], v[202:205], v[78:81]
	v_mfma_f32_16x16x32_bf16 v[74:77], v[148:151], v[202:205], v[74:77]
	v_mfma_f32_16x16x32_bf16 v[126:129], v[134:137], v[182:185], v[126:129]
	v_mfma_f32_16x16x32_bf16 v[122:125], v[152:155], v[182:185], v[122:125]
	v_mfma_f32_16x16x32_bf16 v[110:113], v[134:137], v[190:193], v[110:113]
	v_mfma_f32_16x16x32_bf16 v[106:109], v[152:155], v[190:193], v[106:109]
	v_mfma_f32_16x16x32_bf16 v[94:97], v[134:137], v[198:201], v[94:97]
	v_mfma_f32_16x16x32_bf16 v[90:93], v[152:155], v[198:201], v[90:93]
	v_mfma_f32_16x16x32_bf16 v[78:81], v[134:137], v[206:209], v[78:81]
	v_mfma_f32_16x16x32_bf16 v[74:77], v[152:155], v[206:209], v[74:77]
	v_mfma_f32_16x16x32_bf16 v[118:121], v[162:165], v[178:181], v[118:121]
	v_mfma_f32_16x16x32_bf16 v[114:117], v[170:173], v[178:181], v[114:117]
	v_mfma_f32_16x16x32_bf16 v[102:105], v[162:165], v[186:189], v[102:105]
	v_mfma_f32_16x16x32_bf16 v[98:101], v[170:173], v[186:189], v[98:101]
	v_mfma_f32_16x16x32_bf16 v[86:89], v[162:165], v[194:197], v[86:89]
	v_mfma_f32_16x16x32_bf16 v[82:85], v[170:173], v[194:197], v[82:85]
	v_mfma_f32_16x16x32_bf16 v[70:73], v[162:165], v[202:205], v[70:73]
	v_mfma_f32_16x16x32_bf16 v[66:69], v[170:173], v[202:205], v[66:69]
	v_mfma_f32_16x16x32_bf16 v[118:121], v[166:169], v[182:185], v[118:121]
	v_mfma_f32_16x16x32_bf16 v[114:117], v[174:177], v[182:185], v[114:117]
	v_mfma_f32_16x16x32_bf16 v[102:105], v[166:169], v[190:193], v[102:105]
	v_mfma_f32_16x16x32_bf16 v[98:101], v[174:177], v[190:193], v[98:101]
	v_mfma_f32_16x16x32_bf16 v[86:89], v[166:169], v[198:201], v[86:89]
	v_mfma_f32_16x16x32_bf16 v[82:85], v[174:177], v[198:201], v[82:85]
	v_mfma_f32_16x16x32_bf16 v[70:73], v[166:169], v[206:209], v[70:73]
	v_mfma_f32_16x16x32_bf16 v[66:69], v[174:177], v[206:209], v[66:69]
	s_barrier
; #define PG8_STAGEA(bufoff, gbase, voff) PG8_STAGE_X(bufoff, gbase, voff, AUXA)
; #define PG8_STAGEB(bufoff, gbase, voff) PG8_STAGE_X(bufoff, gbase, voff, AUXB)
; #define PG8_LDA(dst, b, h) do { _Pragma("unroll") for (int m = 0; m < 4; ++m) _Pragma("unroll") for (int k = 0; k < 2; ++k) dst[m][k] = *(const PG8_LAS bf16x8*)(lds + PG8_SA(b, h) + aoff + m * 2048 + k * 1024); } while (0)
; #define PG8_MMA(ai, bj, At, Bt) do { if (GEMM_PRIO_MODE == 0) __builtin_amdgcn_s_setprio(1); PG8_MMA_LOOPS \
;         acc[ai][bj][m][n] = __builtin_amdgcn_mfma_f32_16x16x32_bf16(Bt[n][k], At[m][k], acc[ai][bj][m][n], 0, 0, 0); if (GEMM_PRIO_MODE == 0) __builtin_amdgcn_s_setprio(0); } while (0)
; #define PG8_WAIT_V(n) asm volatile("s_waitcnt vmcnt(" #n ")" ::: "memory")
; #define PG8_WAIT_L(n) asm volatile("s_waitcnt lgkmcnt(" #n ")" ::: "memory")
; #define PG8_BAR __builtin_amdgcn_s_barrier()
; #define PG8_SCHED __builtin_amdgcn_sched_barrier(0)
;     ...
;             PG8_LDA(At, 1, 1); PG8_STAGEB(PG8_SB(1, 0), b3, voffB); PG8_STAGEB(PG8_SB(1, 1), b3 + hstepB, voffB); PG8_STAGEA(PG8_SA(1, 0), a3, voffA);
;             PG8_WAIT_V(8); PG8_WAIT_L(0); PG8_BAR; PG8_MMA(1, 0, At, B0); PG8_MMA(1, 1, At, B1); PG8_BAR; PG8_SCHED;
;     ...
;         if constexpr (ALIGN_EPI) { if (wr == 0) PG8_BAR; }
	s_setprio 0
	s_add_u32 s36, s16, 0x8000
	s_addc_u32 s37, s17, 0
	s_add_i32 s83, s83, s38
	v_lshl_add_u64 v[210:211], s[36:37], 0, v[16:17]
	s_mov_b32 m0, s83
	ds_read_b128 v[178:181], v161 offset:49152
	ds_read_b128 v[182:185], v161 offset:50176
	ds_read_b128 v[186:189], v161 offset:51200
	ds_read_b128 v[190:193], v161 offset:52224
	ds_read_b128 v[194:197], v161 offset:53248
	ds_read_b128 v[198:201], v161 offset:54272
	ds_read_b128 v[202:205], v161 offset:55296
	ds_read_b128 v[206:209], v161 offset:56320
	global_load_lds_dwordx4 v[210:211], off
	s_add_i32 m0, s83, 0x2000
	s_add_u32 s16, s16, 0xc000
	v_lshl_add_u64 v[210:211], s[36:37], 0, v[138:139]
	s_addc_u32 s17, s17, 0
	s_add_i32 s36, s90, s38
	global_load_lds_dwordx4 v[210:211], off
	v_lshl_add_u64 v[210:211], s[16:17], 0, v[16:17]
	s_mov_b32 m0, s36
	s_nop 0
	global_load_lds_dwordx4 v[210:211], off
	v_lshl_add_u64 v[210:211], s[16:17], 0, v[138:139]
	s_add_i32 m0, s36, 0x2000
	s_nop 0
	global_load_lds_dwordx4 v[210:211], off
	v_lshl_add_u64 v[210:211], s[26:27], 0, v[142:143]
	s_mov_b32 m0, s50
	s_nop 0
	global_load_lds_dwordx4 v[210:211], off
	v_lshl_add_u64 v[210:211], s[26:27], 0, v[140:141]
	s_mov_b32 m0, s51
	s_nop 0
	global_load_lds_dwordx4 v[210:211], off
	s_waitcnt vmcnt(8)
	s_waitcnt lgkmcnt(0)
	s_nop 0
	s_nop 0
	s_setprio 1
	s_barrier
	v_mfma_f32_16x16x32_bf16 v[62:65], v[130:133], v[178:181], v[62:65]
	v_mfma_f32_16x16x32_bf16 v[58:61], v[148:151], v[178:181], v[58:61]
	v_mfma_f32_16x16x32_bf16 v[46:49], v[130:133], v[186:189], v[46:49]
	v_mfma_f32_16x16x32_bf16 v[42:45], v[148:151], v[186:189], v[42:45]
	v_mfma_f32_16x16x32_bf16 v[30:33], v[130:133], v[194:197], v[30:33]
	v_mfma_f32_16x16x32_bf16 v[26:29], v[148:151], v[194:197], v[26:29]
	v_mfma_f32_16x16x32_bf16 v[12:15], v[130:133], v[202:205], v[12:15]
	v_mfma_f32_16x16x32_bf16 v[8:11], v[148:151], v[202:205], v[8:11]
	v_mfma_f32_16x16x32_bf16 v[62:65], v[134:137], v[182:185], v[62:65]
	v_mfma_f32_16x16x32_bf16 v[58:61], v[152:155], v[182:185], v[58:61]
	v_mfma_f32_16x16x32_bf16 v[46:49], v[134:137], v[190:193], v[46:49]
	v_mfma_f32_16x16x32_bf16 v[42:45], v[152:155], v[190:193], v[42:45]
	v_mfma_f32_16x16x32_bf16 v[30:33], v[134:137], v[198:201], v[30:33]
	v_mfma_f32_16x16x32_bf16 v[26:29], v[152:155], v[198:201], v[26:29]
	v_mfma_f32_16x16x32_bf16 v[12:15], v[134:137], v[206:209], v[12:15]
	v_mfma_f32_16x16x32_bf16 v[8:11], v[152:155], v[206:209], v[8:11]
	v_mfma_f32_16x16x32_bf16 v[54:57], v[162:165], v[178:181], v[54:57]
	v_mfma_f32_16x16x32_bf16 v[50:53], v[170:173], v[178:181], v[50:53]
	v_mfma_f32_16x16x32_bf16 v[38:41], v[162:165], v[186:189], v[38:41]
	v_mfma_f32_16x16x32_bf16 v[34:37], v[170:173], v[186:189], v[34:37]
	v_mfma_f32_16x16x32_bf16 v[22:25], v[162:165], v[194:197], v[22:25]
	v_mfma_f32_16x16x32_bf16 v[18:21], v[170:173], v[194:197], v[18:21]
	v_mfma_f32_16x16x32_bf16 v[4:7], v[162:165], v[202:205], v[4:7]
	v_mfma_f32_16x16x32_bf16 v[0:3], v[170:173], v[202:205], v[0:3]
	v_mfma_f32_16x16x32_bf16 v[54:57], v[166:169], v[182:185], v[54:57]
	v_mfma_f32_16x16x32_bf16 v[50:53], v[174:177], v[182:185], v[50:53]
	v_mfma_f32_16x16x32_bf16 v[38:41], v[166:169], v[190:193], v[38:41]
	v_mfma_f32_16x16x32_bf16 v[34:37], v[174:177], v[190:193], v[34:37]
	v_mfma_f32_16x16x32_bf16 v[22:25], v[166:169], v[198:201], v[22:25]
	v_mfma_f32_16x16x32_bf16 v[18:21], v[174:177], v[198:201], v[18:21]
	v_mfma_f32_16x16x32_bf16 v[4:7], v[166:169], v[206:209], v[4:7]
	v_mfma_f32_16x16x32_bf16 v[0:3], v[174:177], v[206:209], v[0:3]
	s_barrier
	s_setprio 0
	s_add_i32 s82, s82, 2
	s_add_u32 s24, s24, 0x10000
	s_addc_u32 s25, s25, 0
	s_add_u32 s0, s0, 0x10000
	s_addc_u32 s1, s1, 0
	s_cmpk_gt_u32 s82, 0xfd
	s_cbranch_scc0 .LBB0_848
	s_and_b64 vcc, exec, s[8:9]
	s_cbranch_vccz .LBB0_851
	s_barrier
